# SSD chunk head: the eight 16-B tile-row loads staged into LDS are issued together (were load, wait, ds_write eight times in series through one 4-register buffer)
# speedup vs baseline: 1.0074x; 1.0074x over previous
; DI void ssd_item(const Params& p, int l, int it, char* smem) {
;     ...
;     asm volatile("s_waitcnt vmcnt(0)" ::: "memory");
;     bf16x8 creg[8];
;     const u16* cr = XBCA + (rbase + pos0 + w * 32 + l32) * 1024 + 768 + g * 128 + h * 8;
; #pragma unroll
;     for (int ks = 0; ks < 4; ++ks) creg[ks] = *(const bf16x8*)(cr + ks * 16);
;     __builtin_amdgcn_sched_barrier(0);
; #pragma unroll
;     for (int i = 0; i < 8; ++i) {
;       const int q = tid + 256 * i, j = q >> 4, ch = q & 15;
;       *(uint4*)&BG[j * 136 + ch * 8] = *(const uint4*)&XBCA[(rbase + pos0 + j) * 1024 + 512 + g * 128 + ch * 8];
;     }
;     if (w == 0) {
;       const float r0 = DT[(rbase + pos0 + 2 * lane) * 16 + dir * 8 + hd] + dtb;
.LBB0_989:
	s_add_u32 s78, s81, s86
	s_addc_u32 s79, s80, 0
	v_lshl_add_u64 v[32:33], v[158:159], 0, s[78:79]
	v_lshlrev_b64 v[32:33], 11, v[32:33]
	s_waitcnt vmcnt(0)
	v_lshl_add_u64 v[36:37], v[200:201], 0, v[32:33]
	global_load_dwordx4 v[32:35], v[36:37], off offset:1536
	global_load_dwordx4 v[136:139], v[36:37], off offset:1568
	global_load_dwordx4 v[132:135], v[36:37], off offset:1600
	global_load_dwordx4 v[128:131], v[36:37], off offset:1632
	v_lshl_add_u64 v[42:43], s[78:79], 0, v[162:163]
	v_lshlrev_b64 v[42:43], 11, v[42:43]
	v_lshl_add_u64 v[42:43], v[160:161], 0, v[42:43]
	global_load_dwordx4 v[64:67], v[42:43], off offset:1024
	v_lshl_add_u64 v[44:45], s[78:79], 0, v[166:167]
	v_lshlrev_b64 v[44:45], 11, v[44:45]
	v_lshl_add_u64 v[44:45], v[160:161], 0, v[44:45]
	global_load_dwordx4 v[68:71], v[44:45], off offset:1024
	v_lshl_add_u64 v[46:47], s[78:79], 0, v[170:171]
	v_lshlrev_b64 v[46:47], 11, v[46:47]
	v_lshl_add_u64 v[46:47], v[160:161], 0, v[46:47]
	global_load_dwordx4 v[72:75], v[46:47], off offset:1024
	v_lshl_add_u64 v[48:49], s[78:79], 0, v[178:179]
	v_lshlrev_b64 v[48:49], 11, v[48:49]
	v_lshl_add_u64 v[48:49], v[160:161], 0, v[48:49]
	global_load_dwordx4 v[76:79], v[48:49], off offset:1024
	v_lshl_add_u64 v[50:51], s[78:79], 0, v[182:183]
	v_lshlrev_b64 v[50:51], 11, v[50:51]
	v_lshl_add_u64 v[50:51], v[160:161], 0, v[50:51]
	global_load_dwordx4 v[80:83], v[50:51], off offset:1024
	v_lshl_add_u64 v[52:53], s[78:79], 0, v[186:187]
	v_lshlrev_b64 v[52:53], 11, v[52:53]
	v_lshl_add_u64 v[52:53], v[160:161], 0, v[52:53]
	global_load_dwordx4 v[84:87], v[52:53], off offset:1024
	v_lshl_add_u64 v[54:55], s[78:79], 0, v[190:191]
	v_lshlrev_b64 v[54:55], 11, v[54:55]
	v_lshl_add_u64 v[54:55], v[160:161], 0, v[54:55]
	global_load_dwordx4 v[88:91], v[54:55], off offset:1024
	v_lshl_add_u64 v[56:57], s[78:79], 0, v[194:195]
	v_lshlrev_b64 v[56:57], 11, v[56:57]
	v_lshl_add_u64 v[56:57], v[160:161], 0, v[56:57]
	global_load_dwordx4 v[92:95], v[56:57], off offset:1024
	s_waitcnt vmcnt(0)
	ds_write_b128 v164, v[64:67]
	ds_write_b128 v168, v[68:71]
	ds_write_b128 v176, v[72:75]
	ds_write_b128 v180, v[76:79]
	ds_write_b128 v184, v[80:83]
	ds_write_b128 v188, v[84:87]
	ds_write_b128 v192, v[88:91]
	ds_write_b128 v196, v[92:95]
	s_and_saveexec_b64 s[0:1], s[38:39]
	s_cbranch_execz .LBB0_996
	v_lshl_add_u64 v[38:39], s[78:79], 0, v[172:173]
	v_lshlrev_b64 v[38:39], 6, v[38:39]
	v_lshl_add_u64 v[38:39], s[72:73], 0, v[38:39]
	global_load_dword v40, v[38:39], off
	s_nop 0
	global_load_dword v38, v[38:39], off offset:64
	s_waitcnt vmcnt(1)
	v_add_f32_e32 v156, v234, v40
	v_cmp_nlt_f32_e32 vcc, s53, v156
	s_and_saveexec_b64 s[34:35], vcc
	s_cbranch_execz .LBB0_992
; DI void ssd_item(const Params& p, int l, int it, char* smem) {
;     ...
;       const float r0 = DT[(rbase + pos0 + 2 * lane) * 16 + dir * 8 + hd] + dtb;
;       const float r1 = DT[(rbase + pos0 + 2 * lane + 1) * 16 + dir * 8 + hd] + dtb;
;       const float dt0 = (r0 > 20.f) ? r0 : log1pf(expf(r0));
;       const float dt1 = (r1 > 20.f) ? r1 : log1pf(expf(r1));
;       const float a0 = dt0 * a, a1 = dt1 * a;
	v_mul_f32_e32 v39, 0x3fb8aa3b, v156
	v_rndne_f32_e32 v40, v39
	v_sub_f32_e32 v41, v39, v40
	v_fma_f32 v39, v156, s2, -v39
	v_fmac_f32_e32 v39, 0x32a5705f, v156
	v_add_f32_e32 v39, v41, v39
	v_cvt_i32_f32_e32 v40, v40
	v_exp_f32_e32 v39, v39
	v_cmp_ngt_f32_e32 vcc, s3, v156
	v_ldexp_f32 v39, v39, v40
	s_nop 0
	v_cndmask_b32_e32 v39, 0, v39, vcc
	v_cmp_nlt_f32_e32 vcc, s58, v156
	s_nop 1
	v_cndmask_b32_e32 v39, v217, v39, vcc
	v_add_f32_e32 v42, 1.0, v39
	v_add_f32_e32 v40, -1.0, v42
	v_sub_f32_e32 v41, v40, v42
	v_add_f32_e32 v41, 1.0, v41
	v_sub_f32_e32 v40, v39, v40
	v_add_f32_e32 v43, v40, v41
	v_frexp_mant_f32_e32 v44, v42
	v_cvt_f64_f32_e32 v[40:41], v42
	v_frexp_exp_i32_f64_e32 v40, v[40:41]
	v_cmp_gt_f32_e32 vcc, s14, v44
	s_nop 1
	v_subbrev_co_u32_e32 v48, vcc, 0, v40, vcc
	v_sub_u32_e32 v40, 0, v48
	v_ldexp_f32 v41, v42, v40
	v_add_f32_e32 v42, -1.0, v41
	v_add_f32_e32 v44, 1.0, v41
	v_ldexp_f32 v40, v43, v40
	v_add_f32_e32 v43, 1.0, v42
	v_add_f32_e32 v45, -1.0, v44
	v_sub_f32_e32 v43, v41, v43
	v_sub_f32_e32 v41, v41, v45
	v_add_f32_e32 v43, v40, v43
	v_add_f32_e32 v40, v40, v41
	v_add_f32_e32 v49, v44, v40
	v_rcp_f32_e32 v51, v49
	v_sub_f32_e32 v41, v44, v49
	v_add_f32_e32 v50, v40, v41
	v_add_f32_e32 v41, v42, v43
	v_mul_f32_e32 v53, v41, v51
	v_sub_f32_e32 v40, v42, v41
	v_mul_f32_e32 v42, v49, v53
	v_fma_f32 v44, v53, v49, -v42
	v_fmac_f32_e32 v44, v53, v50
	v_add_f32_e32 v52, v43, v40
	v_add_f32_e32 v40, v42, v44
	v_sub_f32_e32 v43, v41, v40
	v_pk_add_f32 v[46:47], v[40:41], v[42:43] neg_lo:[0,1] neg_hi:[0,1]
	v_mov_b32_e32 v45, v40
	v_pk_add_f32 v[40:41], v[46:47], v[44:45] neg_lo:[0,1] neg_hi:[0,1]
	v_cmp_neq_f32_e32 vcc, s59, v39
	v_add_f32_e32 v41, v52, v41
	v_add_f32_e32 v40, v40, v41
	v_add_f32_e32 v41, v43, v40
	v_mul_f32_e32 v52, v51, v41
	v_mul_f32_e32 v42, v49, v52
	v_fma_f32 v44, v52, v49, -v42
	v_fmac_f32_e32 v44, v52, v50
	v_sub_f32_e32 v43, v43, v41
	v_add_f32_e32 v49, v40, v43
	v_add_f32_e32 v40, v42, v44
	v_sub_f32_e32 v43, v41, v40
	v_pk_add_f32 v[46:47], v[40:41], v[42:43] neg_lo:[0,1] neg_hi:[0,1]
	v_mov_b32_e32 v45, v40
	v_pk_add_f32 v[40:41], v[46:47], v[44:45] neg_lo:[0,1] neg_hi:[0,1]
	s_nop 0
	v_add_f32_e32 v41, v49, v41
	v_add_f32_e32 v40, v40, v41
	v_add_f32_e32 v41, v53, v52
	v_add_f32_e32 v40, v43, v40
	v_sub_f32_e32 v42, v41, v53
	v_mul_f32_e32 v40, v51, v40
	v_sub_f32_e32 v42, v52, v42
	v_add_f32_e32 v42, v42, v40
	v_add_f32_e32 v44, v41, v42
	v_mul_f32_e32 v45, v44, v44
	v_fmamk_f32 v40, v45, 0x3e9b6dac, v205
	v_fmaak_f32 v175, v45, v40, 0x3f2aaada
	v_cvt_f32_i32_e32 v40, v48
	v_sub_f32_e32 v41, v44, v41
	v_sub_f32_e32 v41, v42, v41
	v_ldexp_f32 v46, v41, 1
	v_mul_f32_e32 v41, v44, v45
	v_ldexp_f32 v43, v44, 1
	v_pk_mul_f32 v[44:45], v[40:41], v[174:175]
	s_nop 0
	v_fma_f32 v42, v40, s15, -v44
	v_fmac_f32_e32 v42, 0xb102e308, v40
	v_pk_add_f32 v[40:41], v[44:45], v[42:43]
	s_nop 0
	v_sub_f32_e32 v43, v41, v43
	v_sub_f32_e32 v43, v45, v43
	v_add_f32_e32 v47, v46, v43
	v_mov_b32_e32 v46, v44
	v_pk_add_f32 v[44:45], v[40:41], v[44:45] neg_lo:[0,1] neg_hi:[0,1]
	v_pk_add_f32 v[48:49], v[40:41], v[46:47]
	v_mov_b32_e32 v43, v40
	v_mov_b32_e32 v45, v49
	v_pk_add_f32 v[50:51], v[42:43], v[44:45] neg_lo:[0,1] neg_hi:[0,1]
	v_pk_add_f32 v[42:43], v[42:43], v[44:45]
	v_mov_b32_e32 v46, v47
	v_pk_add_f32 v[44:45], v[42:43], v[40:41] op_sel:[1,0] op_sel_hi:[0,1] neg_lo:[0,1] neg_hi:[0,1]
	v_pk_add_f32 v[52:53], v[48:49], v[44:45] op_sel_hi:[1,0] neg_lo:[0,1] neg_hi:[0,1]
	v_mov_b32_e32 v48, v49
	v_mov_b32_e32 v49, v43
	v_pk_mov_b32 v[44:45], v[40:41], v[44:45] op_sel:[1,0]
	v_mov_b32_e32 v47, v40
	v_pk_add_f32 v[44:45], v[48:49], v[44:45] neg_lo:[0,1] neg_hi:[0,1]
	v_mov_b32_e32 v52, v50
	v_pk_add_f32 v[40:41], v[46:47], v[44:45] neg_lo:[0,1] neg_hi:[0,1]
	v_mov_b32_e32 v51, v43
	v_pk_add_f32 v[44:45], v[52:53], v[40:41]
	s_nop 0
	v_pk_add_f32 v[46:47], v[44:45], v[44:45] op_sel:[0,1] op_sel_hi:[1,0]
	s_nop 0
	v_pk_add_f32 v[42:43], v[42:43], v[46:47] op_sel:[1,0] op_sel_hi:[0,1]
	v_mov_b32_e32 v45, v42
	v_pk_add_f32 v[48:49], v[44:45], v[50:51] neg_lo:[0,1] neg_hi:[0,1]
	v_mov_b32_e32 v41, v46
	v_sub_f32_e32 v43, v44, v48
	v_pk_add_f32 v[40:41], v[40:41], v[48:49] neg_lo:[0,1] neg_hi:[0,1]
	v_sub_f32_e32 v43, v50, v43
	v_add_f32_e32 v40, v40, v43
	v_add_f32_e32 v40, v40, v41
	v_add_f32_e32 v40, v42, v40
	v_cndmask_b32_e32 v40, v217, v40, vcc
	v_cmp_lt_f32_e64 vcc, |v39|, s12
	s_nop 1
	v_cndmask_b32_e32 v156, v40, v39, vcc
